# branch GEMM K-loop also on scalar-base LDS-DMA addressing (all five GEMM loops converted)
# baseline (speedup 1.0000x reference)
.LBB0_901:
	v_add_u32_e32 v142, s47, v198
	v_add_u32_e32 v158, s48, v198
	s_add_u32 s6, s26, s28
	ds_read_b128 v[130:133], v142
	ds_read_b128 v[134:137], v142 offset:1024
	ds_read_b128 v[138:141], v142 offset:2048
	ds_read_b128 v[142:145], v142 offset:3072
	ds_read_b128 v[146:149], v158
	ds_read_b128 v[150:153], v158 offset:1024
	ds_read_b128 v[154:157], v158 offset:2048
	ds_read_b128 v[158:161], v158 offset:3072
	s_addc_u32 s7, s27, s29
	s_add_u32 s6, s6, 0x100
	s_addc_u32 s7, s7, 0
	s_add_u32 s53, s33, s28
	s_addc_u32 s54, s51, s29
	s_cmpk_eq_i32 s28, 0xf00
	s_cselect_b32 s31, s21, s7
	s_cselect_b32 s30, s49, s6
	s_cselect_b32 s7, s19, s54
	s_cselect_b32 s6, s50, s53
	s_add_i32 m0, s38, 0xc000
	ds_read_b128 v[162:165], v200
	ds_read_b128 v[166:169], v200 offset:1024
	ds_read_b128 v[202:205], v200 offset:2048
	ds_read_b128 v[206:209], v200 offset:3072
	ds_read_b128 v[210:213], v200 offset:4096
	ds_read_b128 v[214:217], v200 offset:5120
	ds_read_b128 v[218:221], v200 offset:6144
	ds_read_b128 v[222:225], v200 offset:7168
	s_add_u32 s98, s26, s28
	s_addc_u32 s99, s27, s29
	global_load_lds_dwordx4 v178, s[98:99]
	s_add_i32 m0, s38, 0xe000
	s_nop 0
	global_load_lds_dwordx4 v180, s[98:99]
	s_waitcnt vmcnt(8)
	s_waitcnt lgkmcnt(0)
	s_barrier
	s_setprio 1
	s_waitcnt lgkmcnt(0)
	v_mfma_f32_16x16x32_bf16 v[126:129], v[130:133], v[162:165], v[126:129]
	v_mfma_f32_16x16x32_bf16 v[122:125], v[138:141], v[162:165], v[122:125]
	v_mfma_f32_16x16x32_bf16 v[110:113], v[130:133], v[202:205], v[110:113]
	v_mfma_f32_16x16x32_bf16 v[106:109], v[138:141], v[202:205], v[106:109]
	v_mfma_f32_16x16x32_bf16 v[94:97], v[130:133], v[210:213], v[94:97]
	v_mfma_f32_16x16x32_bf16 v[90:93], v[138:141], v[210:213], v[90:93]
	v_mfma_f32_16x16x32_bf16 v[78:81], v[130:133], v[218:221], v[78:81]
	v_mfma_f32_16x16x32_bf16 v[74:77], v[138:141], v[218:221], v[74:77]
	v_mfma_f32_16x16x32_bf16 v[126:129], v[134:137], v[166:169], v[126:129]
	v_mfma_f32_16x16x32_bf16 v[122:125], v[142:145], v[166:169], v[122:125]
	v_mfma_f32_16x16x32_bf16 v[110:113], v[134:137], v[206:209], v[110:113]
	v_mfma_f32_16x16x32_bf16 v[106:109], v[142:145], v[206:209], v[106:109]
	v_mfma_f32_16x16x32_bf16 v[94:97], v[134:137], v[214:217], v[94:97]
	v_mfma_f32_16x16x32_bf16 v[90:93], v[142:145], v[214:217], v[90:93]
	v_mfma_f32_16x16x32_bf16 v[78:81], v[134:137], v[222:225], v[78:81]
	v_mfma_f32_16x16x32_bf16 v[74:77], v[142:145], v[222:225], v[74:77]
	s_setprio 0
	s_setprio 1
	v_mfma_f32_16x16x32_bf16 v[118:121], v[146:149], v[162:165], v[118:121]
	v_mfma_f32_16x16x32_bf16 v[114:117], v[154:157], v[162:165], v[114:117]
	v_mfma_f32_16x16x32_bf16 v[102:105], v[146:149], v[202:205], v[102:105]
	v_mfma_f32_16x16x32_bf16 v[98:101], v[154:157], v[202:205], v[98:101]
	v_mfma_f32_16x16x32_bf16 v[86:89], v[146:149], v[210:213], v[86:89]
	v_mfma_f32_16x16x32_bf16 v[82:85], v[154:157], v[210:213], v[82:85]
	v_mfma_f32_16x16x32_bf16 v[70:73], v[146:149], v[218:221], v[70:73]
	v_mfma_f32_16x16x32_bf16 v[66:69], v[154:157], v[218:221], v[66:69]
	v_mfma_f32_16x16x32_bf16 v[118:121], v[150:153], v[166:169], v[118:121]
	v_mfma_f32_16x16x32_bf16 v[114:117], v[158:161], v[166:169], v[114:117]
	v_mfma_f32_16x16x32_bf16 v[102:105], v[150:153], v[206:209], v[102:105]
	v_mfma_f32_16x16x32_bf16 v[98:101], v[158:161], v[206:209], v[98:101]
	v_mfma_f32_16x16x32_bf16 v[86:89], v[150:153], v[214:217], v[86:89]
	v_mfma_f32_16x16x32_bf16 v[82:85], v[158:161], v[214:217], v[82:85]
	v_mfma_f32_16x16x32_bf16 v[70:73], v[150:153], v[222:225], v[70:73]
	v_mfma_f32_16x16x32_bf16 v[66:69], v[158:161], v[222:225], v[66:69]
	s_setprio 0
	s_barrier
	s_add_i32 s53, s47, s36
	s_mov_b32 m0, s53
	ds_read_b128 v[162:165], v200 offset:16384
	ds_read_b128 v[166:169], v200 offset:17408
	ds_read_b128 v[202:205], v200 offset:18432
	ds_read_b128 v[206:209], v200 offset:19456
	ds_read_b128 v[210:213], v200 offset:20480
	ds_read_b128 v[214:217], v200 offset:21504
	ds_read_b128 v[218:221], v200 offset:22528
	ds_read_b128 v[222:225], v200 offset:23552
	global_load_lds_dwordx4 v172, s[6:7]
	s_add_i32 m0, s53, 0x2000
	s_add_u32 s54, s6, 0x80000
	s_addc_u32 s55, s7, 0
	s_add_i32 s53, s48, s36
	global_load_lds_dwordx4 v176, s[6:7]
	s_mov_b32 m0, s53
	s_nop 0
	global_load_lds_dwordx4 v172, s[54:55]
	s_add_i32 m0, s53, 0x2000
	s_nop 0
	global_load_lds_dwordx4 v176, s[54:55]
	s_mov_b32 m0, s38
	s_nop 0
	global_load_lds_dwordx4 v170, s[30:31]
	s_mov_b32 m0, s39
	s_nop 0
	global_load_lds_dwordx4 v174, s[30:31]
	s_waitcnt vmcnt(8)
	s_waitcnt lgkmcnt(0)
	s_barrier
	s_setprio 1
	s_waitcnt lgkmcnt(0)
	v_mfma_f32_16x16x32_bf16 v[62:65], v[130:133], v[162:165], v[62:65]
	v_mfma_f32_16x16x32_bf16 v[58:61], v[138:141], v[162:165], v[58:61]
	v_mfma_f32_16x16x32_bf16 v[46:49], v[130:133], v[202:205], v[46:49]
	v_mfma_f32_16x16x32_bf16 v[42:45], v[138:141], v[202:205], v[42:45]
	v_mfma_f32_16x16x32_bf16 v[30:33], v[130:133], v[210:213], v[30:33]
	v_mfma_f32_16x16x32_bf16 v[26:29], v[138:141], v[210:213], v[26:29]
	v_mfma_f32_16x16x32_bf16 v[14:17], v[130:133], v[218:221], v[14:17]
	v_mfma_f32_16x16x32_bf16 v[10:13], v[138:141], v[218:221], v[10:13]
	v_mfma_f32_16x16x32_bf16 v[62:65], v[134:137], v[166:169], v[62:65]
	v_mfma_f32_16x16x32_bf16 v[58:61], v[142:145], v[166:169], v[58:61]
	v_mfma_f32_16x16x32_bf16 v[46:49], v[134:137], v[206:209], v[46:49]
	v_mfma_f32_16x16x32_bf16 v[42:45], v[142:145], v[206:209], v[42:45]
	v_mfma_f32_16x16x32_bf16 v[30:33], v[134:137], v[214:217], v[30:33]
	v_mfma_f32_16x16x32_bf16 v[26:29], v[142:145], v[214:217], v[26:29]
	v_mfma_f32_16x16x32_bf16 v[14:17], v[134:137], v[222:225], v[14:17]
	v_mfma_f32_16x16x32_bf16 v[10:13], v[142:145], v[222:225], v[10:13]
	s_setprio 0
	s_setprio 1
	v_mfma_f32_16x16x32_bf16 v[54:57], v[146:149], v[162:165], v[54:57]
	v_mfma_f32_16x16x32_bf16 v[50:53], v[154:157], v[162:165], v[50:53]
	v_mfma_f32_16x16x32_bf16 v[38:41], v[146:149], v[202:205], v[38:41]
	v_mfma_f32_16x16x32_bf16 v[34:37], v[154:157], v[202:205], v[34:37]
	v_mfma_f32_16x16x32_bf16 v[22:25], v[146:149], v[210:213], v[22:25]
	v_mfma_f32_16x16x32_bf16 v[18:21], v[154:157], v[210:213], v[18:21]
	v_mfma_f32_16x16x32_bf16 v[6:9], v[146:149], v[218:221], v[6:9]
	v_mfma_f32_16x16x32_bf16 v[2:5], v[154:157], v[218:221], v[2:5]
	v_mfma_f32_16x16x32_bf16 v[54:57], v[150:153], v[166:169], v[54:57]
	v_mfma_f32_16x16x32_bf16 v[50:53], v[158:161], v[166:169], v[50:53]
	v_mfma_f32_16x16x32_bf16 v[38:41], v[150:153], v[206:209], v[38:41]
	v_mfma_f32_16x16x32_bf16 v[34:37], v[158:161], v[206:209], v[34:37]
	v_mfma_f32_16x16x32_bf16 v[22:25], v[150:153], v[214:217], v[22:25]
	v_mfma_f32_16x16x32_bf16 v[18:21], v[158:161], v[214:217], v[18:21]
	v_mfma_f32_16x16x32_bf16 v[6:9], v[150:153], v[222:225], v[6:9]
	v_mfma_f32_16x16x32_bf16 v[2:5], v[158:161], v[222:225], v[2:5]
	s_setprio 0
	s_barrier
	s_add_i32 s53, 0, 0x18000
	s_add_i32 s54, 0, 0x1c000
	v_add_u32_e32 v142, s53, v198
	v_add_u32_e32 v158, s54, v198
	ds_read_b128 v[130:133], v142
	ds_read_b128 v[134:137], v142 offset:1024
	ds_read_b128 v[138:141], v142 offset:2048
	ds_read_b128 v[142:145], v142 offset:3072
	ds_read_b128 v[146:149], v158
	ds_read_b128 v[150:153], v158 offset:1024
	ds_read_b128 v[154:157], v158 offset:2048
	ds_read_b128 v[158:161], v158 offset:3072
	s_add_u32 s30, s30, 0x80000
	s_addc_u32 s31, s31, 0
	s_add_u32 s100, s30, 0xfff80080
	s_addc_u32 s101, s31, -1
	s_mov_b32 m0, s40
	ds_read_b128 v[162:165], v200 offset:32768
	ds_read_b128 v[166:169], v200 offset:33792
	ds_read_b128 v[202:205], v200 offset:34816
	ds_read_b128 v[206:209], v200 offset:35840
	ds_read_b128 v[210:213], v200 offset:36864
	ds_read_b128 v[214:217], v200 offset:37888
	ds_read_b128 v[218:221], v200 offset:38912
	ds_read_b128 v[222:225], v200 offset:39936
	global_load_lds_dwordx4 v170, s[30:31]
	s_mov_b32 m0, s41
	s_nop 0
	global_load_lds_dwordx4 v174, s[30:31]
	s_waitcnt vmcnt(8)
	s_waitcnt lgkmcnt(0)
	s_barrier
	s_setprio 1
	s_waitcnt lgkmcnt(0)
	v_mfma_f32_16x16x32_bf16 v[126:129], v[130:133], v[162:165], v[126:129]
	v_mfma_f32_16x16x32_bf16 v[122:125], v[138:141], v[162:165], v[122:125]
	v_mfma_f32_16x16x32_bf16 v[110:113], v[130:133], v[202:205], v[110:113]
	v_mfma_f32_16x16x32_bf16 v[106:109], v[138:141], v[202:205], v[106:109]
	v_mfma_f32_16x16x32_bf16 v[94:97], v[130:133], v[210:213], v[94:97]
	v_mfma_f32_16x16x32_bf16 v[90:93], v[138:141], v[210:213], v[90:93]
	v_mfma_f32_16x16x32_bf16 v[78:81], v[130:133], v[218:221], v[78:81]
	v_mfma_f32_16x16x32_bf16 v[74:77], v[138:141], v[218:221], v[74:77]
	v_mfma_f32_16x16x32_bf16 v[126:129], v[134:137], v[166:169], v[126:129]
	v_mfma_f32_16x16x32_bf16 v[122:125], v[142:145], v[166:169], v[122:125]
	v_mfma_f32_16x16x32_bf16 v[110:113], v[134:137], v[206:209], v[110:113]
	v_mfma_f32_16x16x32_bf16 v[106:109], v[142:145], v[206:209], v[106:109]
	v_mfma_f32_16x16x32_bf16 v[94:97], v[134:137], v[214:217], v[94:97]
	v_mfma_f32_16x16x32_bf16 v[90:93], v[142:145], v[214:217], v[90:93]
	v_mfma_f32_16x16x32_bf16 v[78:81], v[134:137], v[222:225], v[78:81]
	v_mfma_f32_16x16x32_bf16 v[74:77], v[142:145], v[222:225], v[74:77]
	s_setprio 0
	s_setprio 1
	v_mfma_f32_16x16x32_bf16 v[118:121], v[146:149], v[162:165], v[118:121]
	v_mfma_f32_16x16x32_bf16 v[114:117], v[154:157], v[162:165], v[114:117]
	v_mfma_f32_16x16x32_bf16 v[102:105], v[146:149], v[202:205], v[102:105]
	v_mfma_f32_16x16x32_bf16 v[98:101], v[154:157], v[202:205], v[98:101]
	v_mfma_f32_16x16x32_bf16 v[86:89], v[146:149], v[210:213], v[86:89]
	v_mfma_f32_16x16x32_bf16 v[82:85], v[154:157], v[210:213], v[82:85]
	v_mfma_f32_16x16x32_bf16 v[70:73], v[146:149], v[218:221], v[70:73]
	v_mfma_f32_16x16x32_bf16 v[66:69], v[154:157], v[218:221], v[66:69]
	v_mfma_f32_16x16x32_bf16 v[118:121], v[150:153], v[166:169], v[118:121]
	v_mfma_f32_16x16x32_bf16 v[114:117], v[158:161], v[166:169], v[114:117]
	v_mfma_f32_16x16x32_bf16 v[102:105], v[150:153], v[206:209], v[102:105]
	v_mfma_f32_16x16x32_bf16 v[98:101], v[158:161], v[206:209], v[98:101]
	v_mfma_f32_16x16x32_bf16 v[86:89], v[150:153], v[214:217], v[86:89]
	v_mfma_f32_16x16x32_bf16 v[82:85], v[158:161], v[214:217], v[82:85]
	v_mfma_f32_16x16x32_bf16 v[70:73], v[150:153], v[222:225], v[70:73]
	v_mfma_f32_16x16x32_bf16 v[66:69], v[158:161], v[222:225], v[66:69]
	s_setprio 0
	s_barrier
	s_add_i32 s30, s53, s36
	s_mov_b32 m0, s30
	ds_read_b128 v[162:165], v200 offset:49152
	ds_read_b128 v[166:169], v200 offset:50176
	ds_read_b128 v[202:205], v200 offset:51200
	ds_read_b128 v[206:209], v200 offset:52224
	ds_read_b128 v[210:213], v200 offset:53248
	ds_read_b128 v[214:217], v200 offset:54272
	ds_read_b128 v[218:221], v200 offset:55296
	ds_read_b128 v[222:225], v200 offset:56320
	s_add_u32 s98, s6, 0x80
	s_addc_u32 s99, s7, 0
	global_load_lds_dwordx4 v172, s[98:99]
	s_add_i32 m0, s30, 0x2000
	s_add_u32 s6, s6, 0x80080
	s_addc_u32 s7, s7, 0
	s_add_i32 s30, s54, s36
	global_load_lds_dwordx4 v176, s[98:99]
	s_mov_b32 m0, s30
	s_nop 0
	global_load_lds_dwordx4 v172, s[6:7]
	s_add_i32 m0, s30, 0x2000
	s_nop 0
	global_load_lds_dwordx4 v176, s[6:7]
	s_mov_b32 m0, s44
	s_nop 0
	global_load_lds_dwordx4 v170, s[100:101]
	s_mov_b32 m0, s45
	s_nop 0
	global_load_lds_dwordx4 v174, s[100:101]
	s_waitcnt vmcnt(8)
	s_waitcnt lgkmcnt(0)
	s_barrier
	s_setprio 1
	s_waitcnt lgkmcnt(0)
	v_mfma_f32_16x16x32_bf16 v[62:65], v[130:133], v[162:165], v[62:65]
	v_mfma_f32_16x16x32_bf16 v[58:61], v[138:141], v[162:165], v[58:61]
	v_mfma_f32_16x16x32_bf16 v[46:49], v[130:133], v[202:205], v[46:49]
	v_mfma_f32_16x16x32_bf16 v[42:45], v[138:141], v[202:205], v[42:45]
	v_mfma_f32_16x16x32_bf16 v[30:33], v[130:133], v[210:213], v[30:33]
	v_mfma_f32_16x16x32_bf16 v[26:29], v[138:141], v[210:213], v[26:29]
	v_mfma_f32_16x16x32_bf16 v[14:17], v[130:133], v[218:221], v[14:17]
	v_mfma_f32_16x16x32_bf16 v[10:13], v[138:141], v[218:221], v[10:13]
	v_mfma_f32_16x16x32_bf16 v[62:65], v[134:137], v[166:169], v[62:65]
	v_mfma_f32_16x16x32_bf16 v[58:61], v[142:145], v[166:169], v[58:61]
	v_mfma_f32_16x16x32_bf16 v[46:49], v[134:137], v[206:209], v[46:49]
	v_mfma_f32_16x16x32_bf16 v[42:45], v[142:145], v[206:209], v[42:45]
	v_mfma_f32_16x16x32_bf16 v[30:33], v[134:137], v[214:217], v[30:33]
	v_mfma_f32_16x16x32_bf16 v[26:29], v[142:145], v[214:217], v[26:29]
	v_mfma_f32_16x16x32_bf16 v[14:17], v[134:137], v[222:225], v[14:17]
	v_mfma_f32_16x16x32_bf16 v[10:13], v[142:145], v[222:225], v[10:13]
	s_setprio 0
	s_setprio 1
	v_mfma_f32_16x16x32_bf16 v[54:57], v[146:149], v[162:165], v[54:57]
	v_mfma_f32_16x16x32_bf16 v[50:53], v[154:157], v[162:165], v[50:53]
	v_mfma_f32_16x16x32_bf16 v[38:41], v[146:149], v[202:205], v[38:41]
	v_mfma_f32_16x16x32_bf16 v[34:37], v[154:157], v[202:205], v[34:37]
	v_mfma_f32_16x16x32_bf16 v[22:25], v[146:149], v[210:213], v[22:25]
	v_mfma_f32_16x16x32_bf16 v[18:21], v[154:157], v[210:213], v[18:21]
	v_mfma_f32_16x16x32_bf16 v[6:9], v[146:149], v[218:221], v[6:9]
	v_mfma_f32_16x16x32_bf16 v[2:5], v[154:157], v[218:221], v[2:5]
	v_mfma_f32_16x16x32_bf16 v[54:57], v[150:153], v[166:169], v[54:57]
	v_mfma_f32_16x16x32_bf16 v[50:53], v[158:161], v[166:169], v[50:53]
	v_mfma_f32_16x16x32_bf16 v[38:41], v[150:153], v[206:209], v[38:41]
	v_mfma_f32_16x16x32_bf16 v[34:37], v[158:161], v[206:209], v[34:37]
	v_mfma_f32_16x16x32_bf16 v[22:25], v[150:153], v[214:217], v[22:25]
	v_mfma_f32_16x16x32_bf16 v[18:21], v[158:161], v[214:217], v[18:21]
	v_mfma_f32_16x16x32_bf16 v[6:9], v[150:153], v[222:225], v[6:9]
	v_mfma_f32_16x16x32_bf16 v[2:5], v[158:161], v[222:225], v[2:5]
	s_setprio 0
	s_barrier
	s_add_i32 s52, s52, 2
	s_add_u32 s28, s28, 0x100
	s_addc_u32 s29, s29, 0
	s_cmp_gt_u32 s52, 29
	s_cbranch_scc1 .LBB0_904
